# adds: sample cross-attention V loop: late 5 row loads hoisted above first wait (vmcnt(5)), one load round-trip per iteration instead of two
# baseline (speedup 1.0000x reference)
; __device__ __forceinline__ void cross_sample_item(LAS unsigned char* lds, const bf16* QC, const float* mk, const float* mv, bf16* OC, int b, int hh) {
;     ...
; #pragma unroll 1
;     for (int m0 = 0; m0 < 256; m0 += 16) { f32x4 vv[16];
; #pragma unroll
;         for (int i = 0; i < 16; ++i) vv[i] = *(const f32x4*)(vbp + (size_t)(m0 + i) * 1024);
; #pragma unroll
;         for (int i = 0; i < 16; ++i) { o0 += vv[i] * P[m0 + i]; o1 += vv[i] * P[256 + m0 + i]; } }
.LBB0_1388:
	v_add_co_u32_e32 v44, vcc, 0xffff1000, v6
	v_mov_b32_e32 v12, s4
	s_nop 0
	v_addc_co_u32_e32 v45, vcc, -1, v7, vcc
	v_add_co_u32_e32 v46, vcc, 0xffff2000, v6
	global_load_dwordx4 v[0:3], v[6:7], off
	s_nop 0
	v_addc_co_u32_e32 v47, vcc, -1, v7, vcc
	v_add_co_u32_e32 v52, vcc, 0xffff3000, v6
	ds_read_b128 v[32:35], v12
	s_nop 0
	v_addc_co_u32_e32 v53, vcc, -1, v7, vcc
	v_add_co_u32_e32 v54, vcc, 0xffff4000, v6
	global_load_dwordx4 v[36:39], v[44:45], off
	global_load_dwordx4 v[40:43], v[46:47], off
	v_addc_co_u32_e32 v55, vcc, -1, v7, vcc
	v_add_co_u32_e32 v60, vcc, 0xffff5000, v6
	global_load_dwordx4 v[44:47], v[52:53], off
	global_load_dwordx4 v[48:51], v[54:55], off
	v_addc_co_u32_e32 v61, vcc, -1, v7, vcc
	v_add_co_u32_e32 v62, vcc, 0xffff6000, v6
	s_add_i32 s4, s4, 64
	s_nop 0
	v_addc_co_u32_e32 v63, vcc, -1, v7, vcc
	v_add_co_u32_e32 v68, vcc, 0xffff7000, v6
	global_load_dwordx4 v[52:55], v[60:61], off
	global_load_dwordx4 v[56:59], v[62:63], off
	v_addc_co_u32_e32 v69, vcc, -1, v7, vcc
	v_add_co_u32_e32 v70, vcc, 0xffff8000, v6
	s_add_i32 s5, s5, 16
	s_nop 0
	v_addc_co_u32_e32 v71, vcc, -1, v7, vcc
	v_add_co_u32_e32 v76, vcc, 0xffff9000, v6
	global_load_dwordx4 v[60:63], v[68:69], off
	global_load_dwordx4 v[64:67], v[70:71], off
	v_addc_co_u32_e32 v77, vcc, -1, v7, vcc
	v_add_co_u32_e32 v78, vcc, 0xffffa000, v6
	s_cmpk_lt_u32 s5, 0xf0
	s_nop 0
	v_addc_co_u32_e32 v79, vcc, -1, v7, vcc
	v_add_co_u32_e32 v84, vcc, 0xffffb000, v6
	global_load_dwordx4 v[68:71], v[76:77], off
	global_load_dwordx4 v[72:75], v[78:79], off
	v_addc_co_u32_e32 v85, vcc, -1, v7, vcc
	v_add_co_u32_e32 v86, vcc, 0xffffc000, v6
	v_addc_co_u32_e32 v87, vcc, -1, v7, vcc
	v_add_co_u32_e32 v88, vcc, 0xffffd000, v6
	global_load_dwordx4 v[76:79], v[84:85], off
	global_load_dwordx4 v[80:83], v[86:87], off
	v_addc_co_u32_e32 v89, vcc, -1, v7, vcc
	v_add_co_u32_e32 v90, vcc, s19, v6
	global_load_dwordx4 v[84:87], v[88:89], off
	s_nop 0
	v_addc_co_u32_e32 v91, vcc, -1, v7, vcc
	v_add_co_u32_e32 v92, vcc, 0xfffff000, v6
	s_nop 0
	v_addc_co_u32_e32 v93, vcc, -1, v7, vcc
	global_load_dwordx4 v[92:95], v[92:93], off
	global_load_dwordx4 v[88:91], v[90:91], off
	s_waitcnt vmcnt(5) lgkmcnt(0)
	v_pk_fma_f32 v[22:23], v[38:39], v[32:33], v[22:23] op_sel_hi:[1,0,1]
	v_pk_fma_f32 v[10:11], v[36:37], v[32:33], v[10:11] op_sel_hi:[1,0,1]
	v_pk_fma_f32 v[22:23], v[42:43], v[32:33], v[22:23] op_sel:[0,1,0]
	ds_read_b128 v[96:99], v12 offset:16
	ds_read_b128 v[100:103], v12 offset:32
	ds_read_b128 v[104:107], v12 offset:48
	ds_read_b128 v[108:111], v12 offset:1024
	ds_read_b128 v[112:115], v12 offset:1040
	ds_read_b128 v[116:119], v12 offset:1056
	ds_read_b128 v[120:123], v12 offset:1072
	v_pk_fma_f32 v[10:11], v[40:41], v[32:33], v[10:11] op_sel:[0,1,0]
	s_waitcnt lgkmcnt(0)
	v_pk_fma_f32 v[8:9], v[38:39], v[108:109], v[8:9] op_sel_hi:[1,0,1]
	v_pk_fma_f32 v[4:5], v[36:37], v[108:109], v[4:5] op_sel_hi:[1,0,1]
	v_pk_fma_f32 v[8:9], v[42:43], v[108:109], v[8:9] op_sel:[0,1,0]
	v_pk_fma_f32 v[4:5], v[40:41], v[108:109], v[4:5] op_sel:[0,1,0]
	v_mov_b32_e32 v12, v35
	v_mov_b32_e32 v124, v111
	v_pk_fma_f32 v[22:23], v[46:47], v[34:35], v[22:23] op_sel_hi:[1,0,1]
	v_pk_fma_f32 v[10:11], v[44:45], v[34:35], v[10:11] op_sel_hi:[1,0,1]
	v_pk_fma_f32 v[8:9], v[46:47], v[110:111], v[8:9] op_sel_hi:[1,0,1]
	v_pk_fma_f32 v[4:5], v[44:45], v[110:111], v[4:5] op_sel_hi:[1,0,1]
	v_pk_fma_f32 v[22:23], v[50:51], v[12:13], v[22:23] op_sel_hi:[1,0,1]
	v_pk_fma_f32 v[10:11], v[48:49], v[12:13], v[10:11] op_sel_hi:[1,0,1]
	v_pk_fma_f32 v[8:9], v[50:51], v[124:125], v[8:9] op_sel_hi:[1,0,1]
	v_pk_fma_f32 v[4:5], v[48:49], v[124:125], v[4:5] op_sel_hi:[1,0,1]
	v_pk_fma_f32 v[22:23], v[54:55], v[96:97], v[22:23] op_sel_hi:[1,0,1]
	v_pk_fma_f32 v[10:11], v[52:53], v[96:97], v[10:11] op_sel_hi:[1,0,1]
	v_pk_fma_f32 v[8:9], v[54:55], v[112:113], v[8:9] op_sel_hi:[1,0,1]
	v_pk_fma_f32 v[4:5], v[52:53], v[112:113], v[4:5] op_sel_hi:[1,0,1]
	v_pk_fma_f32 v[22:23], v[58:59], v[96:97], v[22:23] op_sel:[0,1,0]
	v_pk_fma_f32 v[10:11], v[56:57], v[96:97], v[10:11] op_sel:[0,1,0]
	v_pk_fma_f32 v[8:9], v[58:59], v[112:113], v[8:9] op_sel:[0,1,0]
	v_pk_fma_f32 v[4:5], v[56:57], v[112:113], v[4:5] op_sel:[0,1,0]
	v_mov_b32_e32 v126, v99
	v_mov_b32_e32 v128, v115
	v_pk_fma_f32 v[22:23], v[62:63], v[98:99], v[22:23] op_sel_hi:[1,0,1]
	v_pk_fma_f32 v[10:11], v[60:61], v[98:99], v[10:11] op_sel_hi:[1,0,1]
	v_pk_fma_f32 v[8:9], v[62:63], v[114:115], v[8:9] op_sel_hi:[1,0,1]
	v_pk_fma_f32 v[4:5], v[60:61], v[114:115], v[4:5] op_sel_hi:[1,0,1]
	v_pk_fma_f32 v[22:23], v[66:67], v[126:127], v[22:23] op_sel_hi:[1,0,1]
	v_pk_fma_f32 v[10:11], v[64:65], v[126:127], v[10:11] op_sel_hi:[1,0,1]
	v_pk_fma_f32 v[8:9], v[66:67], v[128:129], v[8:9] op_sel_hi:[1,0,1]
	v_pk_fma_f32 v[4:5], v[64:65], v[128:129], v[4:5] op_sel_hi:[1,0,1]
	v_pk_fma_f32 v[22:23], v[70:71], v[100:101], v[22:23] op_sel_hi:[1,0,1]
	v_pk_fma_f32 v[10:11], v[68:69], v[100:101], v[10:11] op_sel_hi:[1,0,1]
	v_pk_fma_f32 v[8:9], v[70:71], v[116:117], v[8:9] op_sel_hi:[1,0,1]
	v_pk_fma_f32 v[4:5], v[68:69], v[116:117], v[4:5] op_sel_hi:[1,0,1]
	v_pk_fma_f32 v[22:23], v[74:75], v[100:101], v[22:23] op_sel:[0,1,0]
	v_pk_fma_f32 v[10:11], v[72:73], v[100:101], v[10:11] op_sel:[0,1,0]
	v_pk_fma_f32 v[8:9], v[74:75], v[116:117], v[8:9] op_sel:[0,1,0]
	v_pk_fma_f32 v[4:5], v[72:73], v[116:117], v[4:5] op_sel:[0,1,0]
	v_mov_b32_e32 v130, v103
	v_mov_b32_e32 v132, v119
	v_mov_b32_e32 v134, v107
	v_mov_b32_e32 v136, v123
	v_lshl_add_u64 v[6:7], v[6:7], 0, s[12:13]
	s_waitcnt vmcnt(0)
; __device__ __forceinline__ unsigned pk2(float lo, float hi) { const f32x2 v = {lo, hi}; return __builtin_bit_cast(unsigned, __builtin_convertvector(v, bf16x2_t)); }
; __device__ __forceinline__ float wave_sum(float v) { v += swz_xor<1>(v); v += swz_xor<2>(v); v += swz_xor<4>(v); v += swz_xor<8>(v); v += swz_xor<16>(v); return half_sum(v); }
; __device__ __forceinline__ void cross_sample_item(LAS unsigned char* lds, const bf16* QC, const float* mk, const float* mv, bf16* OC, int b, int hh) {
;     ...
;     sm0 = wave_sum(sm0); sm1 = wave_sum(sm1);
;     ...
;         for (int i = 0; i < 16; ++i) vv[i] = *(const f32x4*)(vbp + (size_t)(m0 + i) * 1024);
; #pragma unroll
;         for (int i = 0; i < 16; ++i) { o0 += vv[i] * P[m0 + i]; o1 += vv[i] * P[256 + m0 + i]; } }
;     const float i0 = 1.f / sm0, i1 = 1.f / sm1; o0 = o0 * i0; o1 = o1 * i1;
;     u32x2 w0, w1; w0.x = pk2(o0.x, o0.y); w0.y = pk2(o0.z, o0.w); w1.x = pk2(o1.x, o1.y); w1.y = pk2(o1.z, o1.w);
;     *(u32x2*)(OC + (size_t)(rowbase + t0) * 1024 + hh * 256 + 4 * lane) = w0; *(u32x2*)(OC + (size_t)(rowbase + t0 + 1) * 1024 + hh * 256 + 4 * lane) = w1;
;     __syncthreads();
	v_pk_fma_f32 v[22:23], v[78:79], v[102:103], v[22:23] op_sel_hi:[1,0,1]
	v_pk_fma_f32 v[10:11], v[76:77], v[102:103], v[10:11] op_sel_hi:[1,0,1]
	v_pk_fma_f32 v[8:9], v[78:79], v[118:119], v[8:9] op_sel_hi:[1,0,1]
	v_pk_fma_f32 v[4:5], v[76:77], v[118:119], v[4:5] op_sel_hi:[1,0,1]
	v_pk_fma_f32 v[22:23], v[82:83], v[130:131], v[22:23] op_sel_hi:[1,0,1]
	v_pk_fma_f32 v[10:11], v[80:81], v[130:131], v[10:11] op_sel_hi:[1,0,1]
	v_pk_fma_f32 v[8:9], v[82:83], v[132:133], v[8:9] op_sel_hi:[1,0,1]
	v_pk_fma_f32 v[4:5], v[80:81], v[132:133], v[4:5] op_sel_hi:[1,0,1]
	v_pk_fma_f32 v[22:23], v[86:87], v[104:105], v[22:23] op_sel_hi:[1,0,1]
	v_pk_fma_f32 v[10:11], v[84:85], v[104:105], v[10:11] op_sel_hi:[1,0,1]
	v_pk_fma_f32 v[8:9], v[86:87], v[120:121], v[8:9] op_sel_hi:[1,0,1]
	v_pk_fma_f32 v[4:5], v[84:85], v[120:121], v[4:5] op_sel_hi:[1,0,1]
	v_pk_fma_f32 v[22:23], v[90:91], v[104:105], v[22:23] op_sel:[0,1,0]
	v_pk_fma_f32 v[10:11], v[88:89], v[104:105], v[10:11] op_sel:[0,1,0]
	v_pk_fma_f32 v[8:9], v[90:91], v[120:121], v[8:9] op_sel:[0,1,0]
	v_pk_fma_f32 v[4:5], v[88:89], v[120:121], v[4:5] op_sel:[0,1,0]
	v_pk_fma_f32 v[22:23], v[94:95], v[106:107], v[22:23] op_sel_hi:[1,0,1]
	v_pk_fma_f32 v[10:11], v[92:93], v[106:107], v[10:11] op_sel_hi:[1,0,1]
	v_pk_fma_f32 v[8:9], v[94:95], v[122:123], v[8:9] op_sel_hi:[1,0,1]
	v_pk_fma_f32 v[4:5], v[92:93], v[122:123], v[4:5] op_sel_hi:[1,0,1]
	v_pk_fma_f32 v[22:23], v[2:3], v[134:135], v[22:23] op_sel_hi:[1,0,1]
	v_pk_fma_f32 v[10:11], v[0:1], v[134:135], v[10:11] op_sel_hi:[1,0,1]
	v_pk_fma_f32 v[8:9], v[2:3], v[136:137], v[8:9] op_sel_hi:[1,0,1]
	v_pk_fma_f32 v[4:5], v[0:1], v[136:137], v[4:5] op_sel_hi:[1,0,1]
	s_cbranch_scc1 .LBB0_1388
	v_add_f32_e32 v0, v25, v28
	v_add_f32_e32 v1, v29, v30
	ds_swizzle_b32 v3, v0 offset:swizzle(SWAP,16)
	ds_swizzle_b32 v2, v1 offset:swizzle(SWAP,16)
	s_lshl_b32 s14, s29, 1
	s_waitcnt lgkmcnt(1)
	v_add_f32_e32 v0, v0, v3
	s_waitcnt lgkmcnt(0)
	v_add_f32_e32 v1, v1, v2
	v_mov_b32_e32 v2, v0
	s_nop 1
	v_permlane32_swap_b32_e32 v0, v2
	v_add_f32_e32 v0, v0, v2
	v_div_scale_f32 v2, s[4:5], v0, v0, 1.0
	v_rcp_f32_e32 v6, v2
	v_mov_b32_e32 v3, v1
	s_nop 1
	v_permlane32_swap_b32_e32 v1, v3
	v_add_f32_e32 v1, v1, v3
	v_fma_f32 v3, -v2, v6, 1.0
	v_fmac_f32_e32 v6, v3, v6
	v_div_scale_f32 v3, vcc, 1.0, v0, 1.0
	v_mul_f32_e32 v7, v3, v6
	v_fma_f32 v12, -v2, v7, v3
	v_fmac_f32_e32 v7, v12, v6
	v_fma_f32 v2, -v2, v7, v3
	v_div_scale_f32 v3, s[4:5], v1, v1, 1.0
	v_rcp_f32_e32 v12, v3
	s_add_i32 s4, s14, s27
	s_ashr_i32 s5, s4, 31
	s_lshl_b64 s[14:15], s[4:5], 11
	v_div_fmas_f32 v2, v2, v6, v7
	s_add_u32 s5, s7, s14
	v_div_fixup_f32 v0, v2, v0, 1.0
	v_fma_f32 v2, -v3, v12, 1.0
	s_addc_u32 s15, s16, s15
	s_lshl_b32 s26, s26, 1
	v_fmac_f32_e32 v12, v2, v12
	v_div_scale_f32 v2, vcc, 1.0, v1, 1.0
	s_add_u32 s14, s5, s26
	v_mul_f32_e32 v6, v2, v12
	s_addc_u32 s15, s15, 0
	s_or_b32 s4, s4, 1
	v_fma_f32 v7, -v3, v6, v2
	s_ashr_i32 s5, s4, 31
	v_fmac_f32_e32 v6, v7, v12
	s_lshl_b64 s[4:5], s[4:5], 11
	v_fma_f32 v2, -v3, v6, v2
	s_add_u32 s4, s7, s4
	v_div_fmas_f32 v2, v2, v12, v6
	s_addc_u32 s5, s16, s5
	v_div_fixup_f32 v2, v2, v1, 1.0
	v_pk_mul_f32 v[6:7], v[22:23], v[0:1] op_sel_hi:[1,0]
	v_pk_mul_f32 v[0:1], v[10:11], v[0:1] op_sel_hi:[1,0]
	v_lshlrev_b32_e32 v12, 3, v24
	s_add_u32 s4, s4, s26
	v_pk_mul_f32 v[8:9], v[8:9], v[2:3] op_sel_hi:[1,0]
	v_pk_mul_f32 v[2:3], v[4:5], v[2:3] op_sel_hi:[1,0]
	v_cvt_pk_bf16_f32 v0, v0, v1
	v_cvt_pk_bf16_f32 v1, v6, v7
	v_lshl_add_u64 v[4:5], s[14:15], 0, v[12:13]
	s_addc_u32 s5, s5, 0
	v_cvt_pk_bf16_f32 v2, v2, v3
	v_cvt_pk_bf16_f32 v3, v8, v9
	global_store_dwordx2 v[4:5], v[0:1], off
	v_lshl_add_u64 v[0:1], s[4:5], 0, v[12:13]
	global_store_dwordx2 v[0:1], v[2:3], off
	s_waitcnt lgkmcnt(0)
	s_barrier
	s_branch .LBB0_1363
